# one static s_setprio 1 for waves 4-7 at kernel entry, all per-block setprio flips in the four GEMM K-loops removed
# baseline (speedup 1.0000x reference)
_Z8hymba_mk6Params:
	v_and_b32_e32 v139, 0x3ff, v0
	v_readfirstlane_b32 s3, v0
	s_bitcmp1_b32 s3, 8
	s_cbranch_scc0 .Lprio_young_skip
	s_setprio 1
.Lprio_young_skip:
	v_writelane_b32 v253, s2, 0
	v_writelane_b32 v253, s0, 1
	s_load_dwordx4 s[64:67], s[0:1], 0xb0
	v_cmp_gt_u32_e32 vcc, 2, v139
	v_writelane_b32 v253, s1, 2
	s_and_saveexec_b64 s[0:1], vcc
	v_lshl_add_u32 v1, v139, 2, 0
	v_add_u32_e32 v1, 0x23fc0, v1
	v_mov_b32_e32 v2, 0
	ds_write_b32 v1, v2
	s_or_b64 exec, exec, s[0:1]
	s_waitcnt lgkmcnt(0)
	s_barrier
	s_add_u32 s0, s64, 0x1f01c400
	s_getreg_b32 s2, hwreg(HW_REG_XCC_ID, 0, 4)
	s_addc_u32 s1, s65, 0
	s_and_b32 s10, s2, 15
	v_cmp_eq_u32_e64 s[4:5], 0, v139
	s_mov_b64 s[2:3], exec
	s_nop 0
	v_writelane_b32 v253, s4, 3
	s_nop 1
	v_writelane_b32 v253, s5, 4
	s_and_b64 s[4:5], s[2:3], s[4:5]
	s_mov_b64 exec, s[4:5]
	s_cbranch_execz .LBB0_5
	s_mov_b64 s[4:5], exec
	v_mbcnt_lo_u32_b32 v1, s4, 0
	v_mbcnt_hi_u32_b32 v1, s5, v1
	v_cmp_eq_u32_e32 vcc, 0, v1
	s_and_b64 s[6:7], exec, vcc
	s_mov_b64 exec, s[6:7]
	s_cbranch_execz .LBB0_5
	s_lshl_b32 s6, s10, 8
	s_bcnt1_i32_b64 s4, s[4:5]
	v_mov_b32_e32 v1, s6
	v_mov_b32_e32 v2, s4
	global_atomic_add v1, v2, s[0:1] offset:1024

.LBB0_98:
	s_add_u32 s18, s44, 0xfffc0080
	s_addc_u32 s19, s45, -1
	s_add_i32 s46, 0, 0x10000
	s_cmp_eq_u32 s15, 12
	s_cselect_b32 s25, s7, s19
	s_cselect_b32 s24, s10, s18
	v_add_u32_e32 v148, s46, v150
	s_cselect_b32 s23, s5, s14
	s_cselect_b32 s22, s11, s13
	s_add_i32 s47, 0, 0x14000
	ds_read_b128 v[156:159], v148
	ds_read_b128 v[160:163], v148 offset:1024
	ds_read_b128 v[164:167], v148 offset:2048
	ds_read_b128 v[168:171], v148 offset:3072
	v_add_u32_e32 v148, s47, v150
	ds_read_b128 v[172:175], v148
	ds_read_b128 v[176:179], v148 offset:1024
	ds_read_b128 v[180:183], v148 offset:2048
	ds_read_b128 v[184:187], v148 offset:3072
	v_lshl_add_u64 v[148:149], s[44:45], 0, v[144:145]
	s_add_i32 m0, s29, 0xc000
	ds_read_b128 v[208:211], v155
	ds_read_b128 v[212:215], v155 offset:1024
	ds_read_b128 v[216:219], v155 offset:2048
	ds_read_b128 v[220:223], v155 offset:3072
	ds_read_b128 v[224:227], v155 offset:4096
	ds_read_b128 v[228:231], v155 offset:5120
	ds_read_b128 v[232:235], v155 offset:6144
	ds_read_b128 v[236:239], v155 offset:7168
	global_load_lds_dwordx4 v[148:149], off
	v_lshl_add_u64 v[148:149], s[44:45], 0, v[146:147]
	s_add_i32 m0, s29, 0xe000
	s_nop 0
	global_load_lds_dwordx4 v[148:149], off
	s_waitcnt vmcnt(8)
	s_waitcnt lgkmcnt(0)
	s_barrier
	s_waitcnt lgkmcnt(0)
	v_mfma_f32_16x16x32_bf16 v[128:131], v[156:159], v[208:211], v[128:131]
	v_mfma_f32_16x16x32_bf16 v[120:123], v[164:167], v[208:211], v[120:123]
	v_mfma_f32_16x16x32_bf16 v[112:115], v[156:159], v[216:219], v[112:115]
	v_mfma_f32_16x16x32_bf16 v[104:107], v[164:167], v[216:219], v[104:107]
	v_mfma_f32_16x16x32_bf16 v[96:99], v[156:159], v[224:227], v[96:99]
	v_mfma_f32_16x16x32_bf16 v[88:91], v[164:167], v[224:227], v[88:91]
	v_mfma_f32_16x16x32_bf16 v[80:83], v[156:159], v[232:235], v[80:83]
	v_mfma_f32_16x16x32_bf16 v[72:75], v[164:167], v[232:235], v[72:75]
	v_mfma_f32_16x16x32_bf16 v[128:131], v[160:163], v[212:215], v[128:131]
	v_mfma_f32_16x16x32_bf16 v[120:123], v[168:171], v[212:215], v[120:123]
	v_mfma_f32_16x16x32_bf16 v[112:115], v[160:163], v[220:223], v[112:115]
	v_mfma_f32_16x16x32_bf16 v[104:107], v[168:171], v[220:223], v[104:107]
	v_mfma_f32_16x16x32_bf16 v[96:99], v[160:163], v[228:231], v[96:99]
	v_mfma_f32_16x16x32_bf16 v[88:91], v[168:171], v[228:231], v[88:91]
	v_mfma_f32_16x16x32_bf16 v[80:83], v[160:163], v[236:239], v[80:83]
	v_mfma_f32_16x16x32_bf16 v[72:75], v[168:171], v[236:239], v[72:75]
	v_mfma_f32_16x16x32_bf16 v[124:127], v[172:175], v[208:211], v[124:127]
	v_mfma_f32_16x16x32_bf16 v[116:119], v[180:183], v[208:211], v[116:119]
	v_mfma_f32_16x16x32_bf16 v[108:111], v[172:175], v[216:219], v[108:111]
	v_mfma_f32_16x16x32_bf16 v[100:103], v[180:183], v[216:219], v[100:103]
	v_mfma_f32_16x16x32_bf16 v[92:95], v[172:175], v[224:227], v[92:95]
	v_mfma_f32_16x16x32_bf16 v[84:87], v[180:183], v[224:227], v[84:87]
	v_mfma_f32_16x16x32_bf16 v[76:79], v[172:175], v[232:235], v[76:79]
	v_mfma_f32_16x16x32_bf16 v[68:71], v[180:183], v[232:235], v[68:71]
	v_mfma_f32_16x16x32_bf16 v[124:127], v[176:179], v[212:215], v[124:127]
	v_mfma_f32_16x16x32_bf16 v[116:119], v[184:187], v[212:215], v[116:119]
	v_mfma_f32_16x16x32_bf16 v[108:111], v[176:179], v[220:223], v[108:111]
	v_mfma_f32_16x16x32_bf16 v[100:103], v[184:187], v[220:223], v[100:103]
	v_mfma_f32_16x16x32_bf16 v[92:95], v[176:179], v[228:231], v[92:95]
	v_mfma_f32_16x16x32_bf16 v[84:87], v[184:187], v[228:231], v[84:87]
	v_mfma_f32_16x16x32_bf16 v[76:79], v[176:179], v[236:239], v[76:79]
	v_mfma_f32_16x16x32_bf16 v[68:71], v[184:187], v[236:239], v[68:71]
	s_barrier
	s_add_i32 s18, s46, s28
	v_lshl_add_u64 v[148:149], s[22:23], 0, v[2:3]
	s_mov_b32 m0, s18
	ds_read_b128 v[208:211], v155 offset:16384
	ds_read_b128 v[212:215], v155 offset:17408
	ds_read_b128 v[216:219], v155 offset:18432
	ds_read_b128 v[220:223], v155 offset:19456
	ds_read_b128 v[224:227], v155 offset:20480
	ds_read_b128 v[228:231], v155 offset:21504
	ds_read_b128 v[232:235], v155 offset:22528
	ds_read_b128 v[236:239], v155 offset:23552
	global_load_lds_dwordx4 v[148:149], off
	s_add_i32 m0, s18, 0x2000
	s_add_u32 s18, s22, 0x40000
	v_lshl_add_u64 v[188:189], s[22:23], 0, v[142:143]
	s_addc_u32 s19, s23, 0
	s_add_i32 s46, s47, s28
	global_load_lds_dwordx4 v[188:189], off
	v_lshl_add_u64 v[196:197], s[18:19], 0, v[2:3]
	s_mov_b32 m0, s46
	v_lshl_add_u64 v[198:199], s[24:25], 0, v[140:141]
	global_load_lds_dwordx4 v[196:197], off
	v_lshl_add_u64 v[196:197], s[18:19], 0, v[142:143]
	s_add_i32 m0, s46, 0x2000
	s_nop 0
	global_load_lds_dwordx4 v[196:197], off
	v_lshl_add_u64 v[196:197], s[24:25], 0, v[0:1]
	s_mov_b32 m0, s29
	s_nop 0
	global_load_lds_dwordx4 v[196:197], off
	s_mov_b32 m0, s43
	s_nop 0
	global_load_lds_dwordx4 v[198:199], off
	s_waitcnt vmcnt(8)
	s_waitcnt lgkmcnt(0)
	s_barrier
	s_waitcnt lgkmcnt(0)
	v_mfma_f32_16x16x32_bf16 v[64:67], v[156:159], v[208:211], v[64:67]
	v_mfma_f32_16x16x32_bf16 v[56:59], v[164:167], v[208:211], v[56:59]
	v_mfma_f32_16x16x32_bf16 v[48:51], v[156:159], v[216:219], v[48:51]
	v_mfma_f32_16x16x32_bf16 v[40:43], v[164:167], v[216:219], v[40:43]
	v_mfma_f32_16x16x32_bf16 v[32:35], v[156:159], v[224:227], v[32:35]
	v_mfma_f32_16x16x32_bf16 v[24:27], v[164:167], v[224:227], v[24:27]
	v_mfma_f32_16x16x32_bf16 v[16:19], v[156:159], v[232:235], v[16:19]
	v_mfma_f32_16x16x32_bf16 v[8:11], v[164:167], v[232:235], v[8:11]
	v_mfma_f32_16x16x32_bf16 v[64:67], v[160:163], v[212:215], v[64:67]
	v_mfma_f32_16x16x32_bf16 v[56:59], v[168:171], v[212:215], v[56:59]
	v_mfma_f32_16x16x32_bf16 v[48:51], v[160:163], v[220:223], v[48:51]
	v_mfma_f32_16x16x32_bf16 v[40:43], v[168:171], v[220:223], v[40:43]
	v_mfma_f32_16x16x32_bf16 v[32:35], v[160:163], v[228:231], v[32:35]
	v_mfma_f32_16x16x32_bf16 v[24:27], v[168:171], v[228:231], v[24:27]
	v_mfma_f32_16x16x32_bf16 v[16:19], v[160:163], v[236:239], v[16:19]
	v_mfma_f32_16x16x32_bf16 v[8:11], v[168:171], v[236:239], v[8:11]
	v_mfma_f32_16x16x32_bf16 v[60:63], v[172:175], v[208:211], v[60:63]
	v_mfma_f32_16x16x32_bf16 v[52:55], v[180:183], v[208:211], v[52:55]
	v_mfma_f32_16x16x32_bf16 v[44:47], v[172:175], v[216:219], v[44:47]
	v_mfma_f32_16x16x32_bf16 v[36:39], v[180:183], v[216:219], v[36:39]
	v_mfma_f32_16x16x32_bf16 v[28:31], v[172:175], v[224:227], v[28:31]
	v_mfma_f32_16x16x32_bf16 v[20:23], v[180:183], v[224:227], v[20:23]
	v_mfma_f32_16x16x32_bf16 v[12:15], v[172:175], v[232:235], v[12:15]
	v_mfma_f32_16x16x32_bf16 v[4:7], v[180:183], v[232:235], v[4:7]
	v_mfma_f32_16x16x32_bf16 v[60:63], v[176:179], v[212:215], v[60:63]
	v_mfma_f32_16x16x32_bf16 v[52:55], v[184:187], v[212:215], v[52:55]
	v_mfma_f32_16x16x32_bf16 v[44:47], v[176:179], v[220:223], v[44:47]
	v_mfma_f32_16x16x32_bf16 v[36:39], v[184:187], v[220:223], v[36:39]
	v_mfma_f32_16x16x32_bf16 v[28:31], v[176:179], v[228:231], v[28:31]
	v_mfma_f32_16x16x32_bf16 v[20:23], v[184:187], v[228:231], v[20:23]
	v_mfma_f32_16x16x32_bf16 v[12:15], v[176:179], v[236:239], v[12:15]
	v_mfma_f32_16x16x32_bf16 v[4:7], v[184:187], v[236:239], v[4:7]
	s_barrier
	s_add_i32 s46, 0, 0x18000
	s_add_i32 s47, 0, 0x1c000
	v_add_u32_e32 v168, s46, v150
	v_add_u32_e32 v184, s47, v150
	ds_read_b128 v[156:159], v168
	ds_read_b128 v[160:163], v168 offset:1024
	ds_read_b128 v[164:167], v168 offset:2048
	ds_read_b128 v[168:171], v168 offset:3072
	ds_read_b128 v[172:175], v184
	ds_read_b128 v[176:179], v184 offset:1024
	ds_read_b128 v[180:183], v184 offset:2048
	ds_read_b128 v[184:187], v184 offset:3072
	s_add_u32 s18, s24, 0x40000
	s_addc_u32 s19, s25, 0
	s_mov_b32 m0, s48
	v_lshl_add_u64 v[200:201], s[18:19], 0, v[0:1]
	ds_read_b128 v[208:211], v155 offset:32768
	ds_read_b128 v[212:215], v155 offset:33792
	ds_read_b128 v[216:219], v155 offset:34816
	ds_read_b128 v[220:223], v155 offset:35840
	ds_read_b128 v[224:227], v155 offset:36864
	ds_read_b128 v[228:231], v155 offset:37888
	ds_read_b128 v[232:235], v155 offset:38912
	ds_read_b128 v[236:239], v155 offset:39936
	global_load_lds_dwordx4 v[200:201], off
	v_lshl_add_u64 v[200:201], s[18:19], 0, v[140:141]
	s_mov_b32 m0, s49
	s_nop 0
	global_load_lds_dwordx4 v[200:201], off
	s_waitcnt vmcnt(8)
	s_waitcnt lgkmcnt(0)
	s_barrier
	s_waitcnt lgkmcnt(0)
	v_mfma_f32_16x16x32_bf16 v[128:131], v[156:159], v[208:211], v[128:131]
	v_mfma_f32_16x16x32_bf16 v[120:123], v[164:167], v[208:211], v[120:123]
	v_mfma_f32_16x16x32_bf16 v[112:115], v[156:159], v[216:219], v[112:115]
	v_mfma_f32_16x16x32_bf16 v[104:107], v[164:167], v[216:219], v[104:107]
	v_mfma_f32_16x16x32_bf16 v[96:99], v[156:159], v[224:227], v[96:99]
	v_mfma_f32_16x16x32_bf16 v[88:91], v[164:167], v[224:227], v[88:91]
	v_mfma_f32_16x16x32_bf16 v[80:83], v[156:159], v[232:235], v[80:83]
	v_mfma_f32_16x16x32_bf16 v[72:75], v[164:167], v[232:235], v[72:75]
	v_mfma_f32_16x16x32_bf16 v[128:131], v[160:163], v[212:215], v[128:131]
	v_mfma_f32_16x16x32_bf16 v[120:123], v[168:171], v[212:215], v[120:123]
	v_mfma_f32_16x16x32_bf16 v[112:115], v[160:163], v[220:223], v[112:115]
	v_mfma_f32_16x16x32_bf16 v[104:107], v[168:171], v[220:223], v[104:107]
	v_mfma_f32_16x16x32_bf16 v[96:99], v[160:163], v[228:231], v[96:99]
	v_mfma_f32_16x16x32_bf16 v[88:91], v[168:171], v[228:231], v[88:91]
	v_mfma_f32_16x16x32_bf16 v[80:83], v[160:163], v[236:239], v[80:83]
	v_mfma_f32_16x16x32_bf16 v[72:75], v[168:171], v[236:239], v[72:75]
	v_mfma_f32_16x16x32_bf16 v[124:127], v[172:175], v[208:211], v[124:127]
	v_mfma_f32_16x16x32_bf16 v[116:119], v[180:183], v[208:211], v[116:119]
	v_mfma_f32_16x16x32_bf16 v[108:111], v[172:175], v[216:219], v[108:111]
	v_mfma_f32_16x16x32_bf16 v[100:103], v[180:183], v[216:219], v[100:103]
	v_mfma_f32_16x16x32_bf16 v[92:95], v[172:175], v[224:227], v[92:95]
	v_mfma_f32_16x16x32_bf16 v[84:87], v[180:183], v[224:227], v[84:87]
	v_mfma_f32_16x16x32_bf16 v[76:79], v[172:175], v[232:235], v[76:79]
	v_mfma_f32_16x16x32_bf16 v[68:71], v[180:183], v[232:235], v[68:71]
	v_mfma_f32_16x16x32_bf16 v[124:127], v[176:179], v[212:215], v[124:127]
	v_mfma_f32_16x16x32_bf16 v[116:119], v[184:187], v[212:215], v[116:119]
	v_mfma_f32_16x16x32_bf16 v[108:111], v[176:179], v[220:223], v[108:111]
	v_mfma_f32_16x16x32_bf16 v[100:103], v[184:187], v[220:223], v[100:103]
	v_mfma_f32_16x16x32_bf16 v[92:95], v[176:179], v[228:231], v[92:95]
	v_mfma_f32_16x16x32_bf16 v[84:87], v[184:187], v[228:231], v[84:87]
	v_mfma_f32_16x16x32_bf16 v[76:79], v[176:179], v[236:239], v[76:79]
	v_mfma_f32_16x16x32_bf16 v[68:71], v[184:187], v[236:239], v[68:71]
	s_barrier
	s_add_i32 s18, s46, s28
	v_lshl_add_u64 v[148:149], v[148:149], 0, s[92:93]
	s_mov_b32 m0, s18
	ds_read_b128 v[208:211], v155 offset:49152
	ds_read_b128 v[212:215], v155 offset:50176
	ds_read_b128 v[216:219], v155 offset:51200
	ds_read_b128 v[220:223], v155 offset:52224
	ds_read_b128 v[224:227], v155 offset:53248
	ds_read_b128 v[228:231], v155 offset:54272
	ds_read_b128 v[232:235], v155 offset:55296
	ds_read_b128 v[236:239], v155 offset:56320
	global_load_lds_dwordx4 v[148:149], off
	s_add_i32 m0, s18, 0x2000
	s_add_u32 s18, s22, 0x40080
	v_lshl_add_u64 v[148:149], v[188:189], 0, s[92:93]
	s_addc_u32 s19, s23, 0
	s_add_i32 s22, s47, s28
	global_load_lds_dwordx4 v[148:149], off
	v_lshl_add_u64 v[148:149], s[18:19], 0, v[2:3]
	s_mov_b32 m0, s22
	s_nop 0
	global_load_lds_dwordx4 v[148:149], off
	v_lshl_add_u64 v[148:149], s[18:19], 0, v[142:143]
	s_add_i32 m0, s22, 0x2000
	s_nop 0
	global_load_lds_dwordx4 v[148:149], off
	v_lshl_add_u64 v[148:149], v[196:197], 0, s[92:93]
	s_mov_b32 m0, s50
	s_nop 0
	global_load_lds_dwordx4 v[148:149], off
	v_lshl_add_u64 v[148:149], v[198:199], 0, s[92:93]
	s_mov_b32 m0, s51
	s_nop 0
	global_load_lds_dwordx4 v[148:149], off
	s_waitcnt vmcnt(8)
	s_waitcnt lgkmcnt(0)
	s_barrier
	s_waitcnt lgkmcnt(0)
	v_mfma_f32_16x16x32_bf16 v[64:67], v[156:159], v[208:211], v[64:67]
	v_mfma_f32_16x16x32_bf16 v[56:59], v[164:167], v[208:211], v[56:59]
	v_mfma_f32_16x16x32_bf16 v[48:51], v[156:159], v[216:219], v[48:51]
	v_mfma_f32_16x16x32_bf16 v[40:43], v[164:167], v[216:219], v[40:43]
	v_mfma_f32_16x16x32_bf16 v[32:35], v[156:159], v[224:227], v[32:35]
	v_mfma_f32_16x16x32_bf16 v[24:27], v[164:167], v[224:227], v[24:27]
	v_mfma_f32_16x16x32_bf16 v[16:19], v[156:159], v[232:235], v[16:19]
	v_mfma_f32_16x16x32_bf16 v[8:11], v[164:167], v[232:235], v[8:11]
	v_mfma_f32_16x16x32_bf16 v[64:67], v[160:163], v[212:215], v[64:67]
	v_mfma_f32_16x16x32_bf16 v[56:59], v[168:171], v[212:215], v[56:59]
	v_mfma_f32_16x16x32_bf16 v[48:51], v[160:163], v[220:223], v[48:51]
	v_mfma_f32_16x16x32_bf16 v[40:43], v[168:171], v[220:223], v[40:43]
	v_mfma_f32_16x16x32_bf16 v[32:35], v[160:163], v[228:231], v[32:35]
	v_mfma_f32_16x16x32_bf16 v[24:27], v[168:171], v[228:231], v[24:27]
	v_mfma_f32_16x16x32_bf16 v[16:19], v[160:163], v[236:239], v[16:19]
	v_mfma_f32_16x16x32_bf16 v[8:11], v[168:171], v[236:239], v[8:11]
	v_mfma_f32_16x16x32_bf16 v[60:63], v[172:175], v[208:211], v[60:63]
	v_mfma_f32_16x16x32_bf16 v[52:55], v[180:183], v[208:211], v[52:55]
	v_mfma_f32_16x16x32_bf16 v[44:47], v[172:175], v[216:219], v[44:47]
	v_mfma_f32_16x16x32_bf16 v[36:39], v[180:183], v[216:219], v[36:39]
	v_mfma_f32_16x16x32_bf16 v[28:31], v[172:175], v[224:227], v[28:31]
	v_mfma_f32_16x16x32_bf16 v[20:23], v[180:183], v[224:227], v[20:23]
	v_mfma_f32_16x16x32_bf16 v[12:15], v[172:175], v[232:235], v[12:15]
	v_mfma_f32_16x16x32_bf16 v[4:7], v[180:183], v[232:235], v[4:7]
	v_mfma_f32_16x16x32_bf16 v[60:63], v[176:179], v[212:215], v[60:63]
	v_mfma_f32_16x16x32_bf16 v[52:55], v[184:187], v[212:215], v[52:55]
	v_mfma_f32_16x16x32_bf16 v[44:47], v[176:179], v[220:223], v[44:47]
	v_mfma_f32_16x16x32_bf16 v[36:39], v[184:187], v[220:223], v[36:39]
	v_mfma_f32_16x16x32_bf16 v[28:31], v[176:179], v[228:231], v[28:31]
	v_mfma_f32_16x16x32_bf16 v[20:23], v[184:187], v[228:231], v[20:23]
	v_mfma_f32_16x16x32_bf16 v[12:15], v[176:179], v[236:239], v[12:15]
	v_mfma_f32_16x16x32_bf16 v[4:7], v[184:187], v[236:239], v[4:7]
	s_barrier
	s_add_i32 s15, s15, 2
	s_add_u32 s44, s44, 0x100
	s_addc_u32 s45, s45, 0
	s_add_u32 s13, s13, 0x100
	s_addc_u32 s14, s14, 0
	s_cmp_gt_u32 s15, 13
	s_cbranch_scc0 .LBB0_98
	s_lshl_b32 s5, s42, 8
	s_and_b64 vcc, exec, s[2:3]
	s_cbranch_vccz .LBB0_101
	v_or_b32_e32 v148, s5, v152
	v_ashrrev_i32_e32 v149, 31, v148
	v_readlane_b32 s10, v255, 11
	v_lshlrev_b64 v[148:149], 6, v[148:149]
	v_readlane_b32 s11, v255, 12
	s_nop 1
	v_lshl_add_u64 v[148:149], s[10:11], 0, v[148:149]
	global_load_dwordx4 v[156:159], v[148:149], off
	global_load_dwordx4 v[160:163], v[148:149], off offset:32
	global_load_dwordx4 v[164:167], v[148:149], off offset:16
	global_load_dwordx4 v[168:171], v[148:149], off offset:48
	s_barrier

.LBB0_504:
	s_add_u32 s10, s16, s44
	s_addc_u32 s11, s17, s45
	s_add_u32 s10, s10, 0x100
	s_addc_u32 s11, s11, 0
	s_add_u32 s18, s13, s44
	s_addc_u32 s19, s14, s45
	s_cmpk_eq_i32 s44, 0xb00
	s_cselect_b32 s25, s5, s11
	s_cselect_b32 s24, s4, s10
	s_cselect_b32 s23, s7, s19
	s_cselect_b32 s22, s6, s18
	s_add_i32 s10, 0, 0x10000
	v_add_u32_e32 v0, s10, v208
	s_add_i32 s18, 0, 0x14000
	ds_read_b128 v[162:165], v0
	ds_read_b128 v[166:169], v0 offset:1024
	ds_read_b128 v[170:173], v0 offset:2048
	ds_read_b128 v[174:177], v0 offset:3072
	v_add_u32_e32 v0, s18, v208
	ds_read_b128 v[178:181], v0
	ds_read_b128 v[182:185], v0 offset:1024
	ds_read_b128 v[212:215], v0 offset:2048
	ds_read_b128 v[216:219], v0 offset:3072
	v_lshl_add_u64 v[0:1], v[158:159], 0, s[44:45]
	s_add_i32 m0, s47, 0xc000
	ds_read_b128 v[220:223], v211
	ds_read_b128 v[224:227], v211 offset:1024
	ds_read_b128 v[228:231], v211 offset:2048
	ds_read_b128 v[232:235], v211 offset:3072
	ds_read_b128 v[236:239], v211 offset:4096
	ds_read_b128 v[240:243], v211 offset:5120
	ds_read_b128 v[244:247], v211 offset:6144
	ds_read_b128 v[248:251], v211 offset:7168
	global_load_lds_dwordx4 v[0:1], off
	v_lshl_add_u64 v[0:1], v[160:161], 0, s[44:45]
	s_add_i32 m0, s47, 0xe000
	s_nop 0
	global_load_lds_dwordx4 v[0:1], off
	s_waitcnt vmcnt(8)
	s_waitcnt lgkmcnt(0)
	s_barrier
	s_waitcnt lgkmcnt(0)
	v_mfma_f32_16x16x32_bf16 v[128:131], v[162:165], v[220:223], v[128:131]
	v_mfma_f32_16x16x32_bf16 v[124:127], v[170:173], v[220:223], v[124:127]
	v_mfma_f32_16x16x32_bf16 v[112:115], v[162:165], v[228:231], v[112:115]
	v_mfma_f32_16x16x32_bf16 v[108:111], v[170:173], v[228:231], v[108:111]
	v_mfma_f32_16x16x32_bf16 v[96:99], v[162:165], v[236:239], v[96:99]
	v_mfma_f32_16x16x32_bf16 v[92:95], v[170:173], v[236:239], v[92:95]
	v_mfma_f32_16x16x32_bf16 v[80:83], v[162:165], v[244:247], v[80:83]
	v_mfma_f32_16x16x32_bf16 v[76:79], v[170:173], v[244:247], v[76:79]
	v_mfma_f32_16x16x32_bf16 v[128:131], v[166:169], v[224:227], v[128:131]
	v_mfma_f32_16x16x32_bf16 v[124:127], v[174:177], v[224:227], v[124:127]
	v_mfma_f32_16x16x32_bf16 v[112:115], v[166:169], v[232:235], v[112:115]
	v_mfma_f32_16x16x32_bf16 v[108:111], v[174:177], v[232:235], v[108:111]
	v_mfma_f32_16x16x32_bf16 v[96:99], v[166:169], v[240:243], v[96:99]
	v_mfma_f32_16x16x32_bf16 v[92:95], v[174:177], v[240:243], v[92:95]
	v_mfma_f32_16x16x32_bf16 v[80:83], v[166:169], v[248:251], v[80:83]
	v_mfma_f32_16x16x32_bf16 v[76:79], v[174:177], v[248:251], v[76:79]
	v_mfma_f32_16x16x32_bf16 v[120:123], v[178:181], v[220:223], v[120:123]
	v_mfma_f32_16x16x32_bf16 v[116:119], v[212:215], v[220:223], v[116:119]
	v_mfma_f32_16x16x32_bf16 v[104:107], v[178:181], v[228:231], v[104:107]
	v_mfma_f32_16x16x32_bf16 v[100:103], v[212:215], v[228:231], v[100:103]
	v_mfma_f32_16x16x32_bf16 v[88:91], v[178:181], v[236:239], v[88:91]
	v_mfma_f32_16x16x32_bf16 v[84:87], v[212:215], v[236:239], v[84:87]
	v_mfma_f32_16x16x32_bf16 v[72:75], v[178:181], v[244:247], v[72:75]
	v_mfma_f32_16x16x32_bf16 v[68:71], v[212:215], v[244:247], v[68:71]
	v_mfma_f32_16x16x32_bf16 v[120:123], v[182:185], v[224:227], v[120:123]
	v_mfma_f32_16x16x32_bf16 v[116:119], v[216:219], v[224:227], v[116:119]
	v_mfma_f32_16x16x32_bf16 v[104:107], v[182:185], v[232:235], v[104:107]
	v_mfma_f32_16x16x32_bf16 v[100:103], v[216:219], v[232:235], v[100:103]
	v_mfma_f32_16x16x32_bf16 v[88:91], v[182:185], v[240:243], v[88:91]
	v_mfma_f32_16x16x32_bf16 v[84:87], v[216:219], v[240:243], v[84:87]
	v_mfma_f32_16x16x32_bf16 v[72:75], v[182:185], v[248:251], v[72:75]
	v_mfma_f32_16x16x32_bf16 v[68:71], v[216:219], v[248:251], v[68:71]
	s_barrier
	s_add_i32 s10, s10, s46
	v_lshl_add_u64 v[0:1], s[22:23], 0, v[140:141]
	s_mov_b32 m0, s10
	ds_read_b128 v[220:223], v211 offset:16384
	ds_read_b128 v[224:227], v211 offset:17408
	ds_read_b128 v[228:231], v211 offset:18432
	ds_read_b128 v[232:235], v211 offset:19456
	ds_read_b128 v[236:239], v211 offset:20480
	ds_read_b128 v[240:243], v211 offset:21504
	ds_read_b128 v[244:247], v211 offset:22528
	ds_read_b128 v[248:251], v211 offset:23552
	global_load_lds_dwordx4 v[0:1], off
	s_add_i32 m0, s10, 0x2000
	s_add_u32 s10, s22, 0x60000
	v_lshl_add_u64 v[186:187], s[22:23], 0, v[142:143]
	s_addc_u32 s11, s23, 0
	s_add_i32 s18, s18, s46
	global_load_lds_dwordx4 v[186:187], off
	v_lshl_add_u64 v[196:197], s[10:11], 0, v[140:141]
	s_mov_b32 m0, s18
	v_lshl_add_u64 v[198:199], s[24:25], 0, v[142:143]
	global_load_lds_dwordx4 v[196:197], off
	v_lshl_add_u64 v[196:197], s[10:11], 0, v[142:143]
	s_add_i32 m0, s18, 0x2000
	s_nop 0
	global_load_lds_dwordx4 v[196:197], off
	v_lshl_add_u64 v[196:197], s[24:25], 0, v[140:141]
	s_mov_b32 m0, s47
	s_nop 0
	global_load_lds_dwordx4 v[196:197], off
	s_mov_b32 m0, s48
	s_nop 0
	global_load_lds_dwordx4 v[198:199], off
	s_waitcnt vmcnt(8)
	s_waitcnt lgkmcnt(0)
	s_barrier
	s_waitcnt lgkmcnt(0)
	v_mfma_f32_16x16x32_bf16 v[64:67], v[162:165], v[220:223], v[64:67]
	v_mfma_f32_16x16x32_bf16 v[60:63], v[170:173], v[220:223], v[60:63]
	v_mfma_f32_16x16x32_bf16 v[48:51], v[162:165], v[228:231], v[48:51]
	v_mfma_f32_16x16x32_bf16 v[44:47], v[170:173], v[228:231], v[44:47]
	v_mfma_f32_16x16x32_bf16 v[32:35], v[162:165], v[236:239], v[32:35]
	v_mfma_f32_16x16x32_bf16 v[28:31], v[170:173], v[236:239], v[28:31]
	v_mfma_f32_16x16x32_bf16 v[16:19], v[162:165], v[244:247], v[16:19]
	v_mfma_f32_16x16x32_bf16 v[12:15], v[170:173], v[244:247], v[12:15]
	v_mfma_f32_16x16x32_bf16 v[64:67], v[166:169], v[224:227], v[64:67]
	v_mfma_f32_16x16x32_bf16 v[60:63], v[174:177], v[224:227], v[60:63]
	v_mfma_f32_16x16x32_bf16 v[48:51], v[166:169], v[232:235], v[48:51]
	v_mfma_f32_16x16x32_bf16 v[44:47], v[174:177], v[232:235], v[44:47]
	v_mfma_f32_16x16x32_bf16 v[32:35], v[166:169], v[240:243], v[32:35]
	v_mfma_f32_16x16x32_bf16 v[28:31], v[174:177], v[240:243], v[28:31]
	v_mfma_f32_16x16x32_bf16 v[16:19], v[166:169], v[248:251], v[16:19]
	v_mfma_f32_16x16x32_bf16 v[12:15], v[174:177], v[248:251], v[12:15]
	v_mfma_f32_16x16x32_bf16 v[56:59], v[178:181], v[220:223], v[56:59]
	v_mfma_f32_16x16x32_bf16 v[52:55], v[212:215], v[220:223], v[52:55]
	v_mfma_f32_16x16x32_bf16 v[40:43], v[178:181], v[228:231], v[40:43]
	v_mfma_f32_16x16x32_bf16 v[36:39], v[212:215], v[228:231], v[36:39]
	v_mfma_f32_16x16x32_bf16 v[24:27], v[178:181], v[236:239], v[24:27]
	v_mfma_f32_16x16x32_bf16 v[20:23], v[212:215], v[236:239], v[20:23]
	v_mfma_f32_16x16x32_bf16 v[8:11], v[178:181], v[244:247], v[8:11]
	v_mfma_f32_16x16x32_bf16 v[4:7], v[212:215], v[244:247], v[4:7]
	v_mfma_f32_16x16x32_bf16 v[56:59], v[182:185], v[224:227], v[56:59]
	v_mfma_f32_16x16x32_bf16 v[52:55], v[216:219], v[224:227], v[52:55]
	v_mfma_f32_16x16x32_bf16 v[40:43], v[182:185], v[232:235], v[40:43]
	v_mfma_f32_16x16x32_bf16 v[36:39], v[216:219], v[232:235], v[36:39]
	v_mfma_f32_16x16x32_bf16 v[24:27], v[182:185], v[240:243], v[24:27]
	v_mfma_f32_16x16x32_bf16 v[20:23], v[216:219], v[240:243], v[20:23]
	v_mfma_f32_16x16x32_bf16 v[8:11], v[182:185], v[248:251], v[8:11]
	v_mfma_f32_16x16x32_bf16 v[4:7], v[216:219], v[248:251], v[4:7]
	s_barrier
	s_add_i32 s18, 0, 0x18000
	v_add_u32_e32 v2, s18, v208
	s_add_i32 s19, 0, 0x1c000
	ds_read_b128 v[162:165], v2
	ds_read_b128 v[166:169], v2 offset:1024
	ds_read_b128 v[170:173], v2 offset:2048
	ds_read_b128 v[174:177], v2 offset:3072
	v_add_u32_e32 v2, s19, v208
	ds_read_b128 v[178:181], v2
	ds_read_b128 v[182:185], v2 offset:1024
	ds_read_b128 v[212:215], v2 offset:2048
	ds_read_b128 v[216:219], v2 offset:3072
	s_add_u32 s10, s24, 0x60000
	s_addc_u32 s11, s25, 0
	s_mov_b32 m0, s49
	v_lshl_add_u64 v[200:201], s[10:11], 0, v[140:141]
	ds_read_b128 v[220:223], v211 offset:32768
	ds_read_b128 v[224:227], v211 offset:33792
	ds_read_b128 v[228:231], v211 offset:34816
	ds_read_b128 v[232:235], v211 offset:35840
	ds_read_b128 v[236:239], v211 offset:36864
	ds_read_b128 v[240:243], v211 offset:37888
	ds_read_b128 v[244:247], v211 offset:38912
	ds_read_b128 v[248:251], v211 offset:39936
	global_load_lds_dwordx4 v[200:201], off
	v_lshl_add_u64 v[200:201], s[10:11], 0, v[142:143]
	s_mov_b32 m0, s50
	s_nop 0
	global_load_lds_dwordx4 v[200:201], off
	s_waitcnt vmcnt(8)
	s_waitcnt lgkmcnt(0)
	s_barrier
	s_waitcnt lgkmcnt(0)
	v_mfma_f32_16x16x32_bf16 v[128:131], v[162:165], v[220:223], v[128:131]
	v_mfma_f32_16x16x32_bf16 v[124:127], v[170:173], v[220:223], v[124:127]
	v_mfma_f32_16x16x32_bf16 v[112:115], v[162:165], v[228:231], v[112:115]
	v_mfma_f32_16x16x32_bf16 v[108:111], v[170:173], v[228:231], v[108:111]
	v_mfma_f32_16x16x32_bf16 v[96:99], v[162:165], v[236:239], v[96:99]
	v_mfma_f32_16x16x32_bf16 v[92:95], v[170:173], v[236:239], v[92:95]
	v_mfma_f32_16x16x32_bf16 v[80:83], v[162:165], v[244:247], v[80:83]
	v_mfma_f32_16x16x32_bf16 v[76:79], v[170:173], v[244:247], v[76:79]
	v_mfma_f32_16x16x32_bf16 v[128:131], v[166:169], v[224:227], v[128:131]
	v_mfma_f32_16x16x32_bf16 v[124:127], v[174:177], v[224:227], v[124:127]
	v_mfma_f32_16x16x32_bf16 v[112:115], v[166:169], v[232:235], v[112:115]
	v_mfma_f32_16x16x32_bf16 v[108:111], v[174:177], v[232:235], v[108:111]
	v_mfma_f32_16x16x32_bf16 v[96:99], v[166:169], v[240:243], v[96:99]
	v_mfma_f32_16x16x32_bf16 v[92:95], v[174:177], v[240:243], v[92:95]
	v_mfma_f32_16x16x32_bf16 v[80:83], v[166:169], v[248:251], v[80:83]
	v_mfma_f32_16x16x32_bf16 v[76:79], v[174:177], v[248:251], v[76:79]
	v_mfma_f32_16x16x32_bf16 v[120:123], v[178:181], v[220:223], v[120:123]
	v_mfma_f32_16x16x32_bf16 v[116:119], v[212:215], v[220:223], v[116:119]
	v_mfma_f32_16x16x32_bf16 v[104:107], v[178:181], v[228:231], v[104:107]
	v_mfma_f32_16x16x32_bf16 v[100:103], v[212:215], v[228:231], v[100:103]
	v_mfma_f32_16x16x32_bf16 v[88:91], v[178:181], v[236:239], v[88:91]
	v_mfma_f32_16x16x32_bf16 v[84:87], v[212:215], v[236:239], v[84:87]
	v_mfma_f32_16x16x32_bf16 v[72:75], v[178:181], v[244:247], v[72:75]
	v_mfma_f32_16x16x32_bf16 v[68:71], v[212:215], v[244:247], v[68:71]
	v_mfma_f32_16x16x32_bf16 v[120:123], v[182:185], v[224:227], v[120:123]
	v_mfma_f32_16x16x32_bf16 v[116:119], v[216:219], v[224:227], v[116:119]
	v_mfma_f32_16x16x32_bf16 v[104:107], v[182:185], v[232:235], v[104:107]
	v_mfma_f32_16x16x32_bf16 v[100:103], v[216:219], v[232:235], v[100:103]
	v_mfma_f32_16x16x32_bf16 v[88:91], v[182:185], v[240:243], v[88:91]
	v_mfma_f32_16x16x32_bf16 v[84:87], v[216:219], v[240:243], v[84:87]
	v_mfma_f32_16x16x32_bf16 v[72:75], v[182:185], v[248:251], v[72:75]
	v_mfma_f32_16x16x32_bf16 v[68:71], v[216:219], v[248:251], v[68:71]
	s_barrier
	s_add_i32 s10, s18, s46
	v_lshl_add_u64 v[0:1], v[0:1], 0, s[92:93]
	s_mov_b32 m0, s10
	ds_read_b128 v[220:223], v211 offset:49152
	ds_read_b128 v[224:227], v211 offset:50176
	ds_read_b128 v[228:231], v211 offset:51200
	ds_read_b128 v[232:235], v211 offset:52224
	ds_read_b128 v[236:239], v211 offset:53248
	ds_read_b128 v[240:243], v211 offset:54272
	ds_read_b128 v[244:247], v211 offset:55296
	ds_read_b128 v[248:251], v211 offset:56320
	global_load_lds_dwordx4 v[0:1], off
	s_add_i32 m0, s10, 0x2000
	s_add_u32 s10, s22, 0x60080
	v_lshl_add_u64 v[0:1], v[186:187], 0, s[92:93]
	s_addc_u32 s11, s23, 0
	s_add_i32 s18, s19, s46
	global_load_lds_dwordx4 v[0:1], off
	v_lshl_add_u64 v[0:1], s[10:11], 0, v[140:141]
	s_mov_b32 m0, s18
	s_nop 0
	global_load_lds_dwordx4 v[0:1], off
	v_lshl_add_u64 v[0:1], s[10:11], 0, v[142:143]
	s_add_i32 m0, s18, 0x2000
	s_nop 0
	global_load_lds_dwordx4 v[0:1], off
	v_lshl_add_u64 v[0:1], v[196:197], 0, s[92:93]
	s_mov_b32 m0, s52
	s_nop 0
	global_load_lds_dwordx4 v[0:1], off
	v_lshl_add_u64 v[0:1], v[198:199], 0, s[92:93]
	s_mov_b32 m0, s53
	s_nop 0
	global_load_lds_dwordx4 v[0:1], off
	s_waitcnt vmcnt(8)
	s_waitcnt lgkmcnt(0)
	s_barrier
	s_waitcnt lgkmcnt(0)
	v_mfma_f32_16x16x32_bf16 v[64:67], v[162:165], v[220:223], v[64:67]
	v_mfma_f32_16x16x32_bf16 v[60:63], v[170:173], v[220:223], v[60:63]
	v_mfma_f32_16x16x32_bf16 v[48:51], v[162:165], v[228:231], v[48:51]
	v_mfma_f32_16x16x32_bf16 v[44:47], v[170:173], v[228:231], v[44:47]
	v_mfma_f32_16x16x32_bf16 v[32:35], v[162:165], v[236:239], v[32:35]
	v_mfma_f32_16x16x32_bf16 v[28:31], v[170:173], v[236:239], v[28:31]
	v_mfma_f32_16x16x32_bf16 v[16:19], v[162:165], v[244:247], v[16:19]
	v_mfma_f32_16x16x32_bf16 v[12:15], v[170:173], v[244:247], v[12:15]
	v_mfma_f32_16x16x32_bf16 v[64:67], v[166:169], v[224:227], v[64:67]
	v_mfma_f32_16x16x32_bf16 v[60:63], v[174:177], v[224:227], v[60:63]
	v_mfma_f32_16x16x32_bf16 v[48:51], v[166:169], v[232:235], v[48:51]
	v_mfma_f32_16x16x32_bf16 v[44:47], v[174:177], v[232:235], v[44:47]
	v_mfma_f32_16x16x32_bf16 v[32:35], v[166:169], v[240:243], v[32:35]
	v_mfma_f32_16x16x32_bf16 v[28:31], v[174:177], v[240:243], v[28:31]
	v_mfma_f32_16x16x32_bf16 v[16:19], v[166:169], v[248:251], v[16:19]
	v_mfma_f32_16x16x32_bf16 v[12:15], v[174:177], v[248:251], v[12:15]
	v_mfma_f32_16x16x32_bf16 v[56:59], v[178:181], v[220:223], v[56:59]
	v_mfma_f32_16x16x32_bf16 v[52:55], v[212:215], v[220:223], v[52:55]
	v_mfma_f32_16x16x32_bf16 v[40:43], v[178:181], v[228:231], v[40:43]
	v_mfma_f32_16x16x32_bf16 v[36:39], v[212:215], v[228:231], v[36:39]
	v_mfma_f32_16x16x32_bf16 v[24:27], v[178:181], v[236:239], v[24:27]
	v_mfma_f32_16x16x32_bf16 v[20:23], v[212:215], v[236:239], v[20:23]
	v_mfma_f32_16x16x32_bf16 v[8:11], v[178:181], v[244:247], v[8:11]
	v_mfma_f32_16x16x32_bf16 v[4:7], v[212:215], v[244:247], v[4:7]
	v_mfma_f32_16x16x32_bf16 v[56:59], v[182:185], v[224:227], v[56:59]
	v_mfma_f32_16x16x32_bf16 v[52:55], v[216:219], v[224:227], v[52:55]
	v_mfma_f32_16x16x32_bf16 v[40:43], v[182:185], v[232:235], v[40:43]
	v_mfma_f32_16x16x32_bf16 v[36:39], v[216:219], v[232:235], v[36:39]
	v_mfma_f32_16x16x32_bf16 v[24:27], v[182:185], v[240:243], v[24:27]
	v_mfma_f32_16x16x32_bf16 v[20:23], v[216:219], v[240:243], v[20:23]
	v_mfma_f32_16x16x32_bf16 v[8:11], v[182:185], v[248:251], v[8:11]
	v_mfma_f32_16x16x32_bf16 v[4:7], v[216:219], v[248:251], v[4:7]
	s_barrier
	s_add_i32 s10, s15, 2
	s_add_u32 s44, s44, 0x100
	s_addc_u32 s45, s45, 0
	s_cmp_gt_u32 s15, 21
	s_cbranch_scc1 .LBB0_513
	s_mov_b32 s15, s10
	s_cmp_lt_i32 s15, 16
	s_cbranch_scc1 .LBB0_490

.LBB0_811:
	s_add_u32 s42, s44, 0x100
	s_addc_u32 s43, s45, 0
	s_add_i32 s18, 0, 0x10000
	s_cmp_eq_u32 s15, 40
	s_cselect_b32 s25, s11, s43
	s_cselect_b32 s24, s10, s42
	s_cselect_b32 s23, s17, s14
	s_cselect_b32 s22, s16, s13
	s_add_i32 s62, 0, 0x14000
	v_add_u32_e32 v156, s18, v210
	v_add_u32_e32 v172, s62, v210
	ds_read_b128 v[144:147], v156
	ds_read_b128 v[148:151], v156 offset:1024
	ds_read_b128 v[152:155], v156 offset:2048
	ds_read_b128 v[156:159], v156 offset:3072
	ds_read_b128 v[160:163], v172
	ds_read_b128 v[164:167], v172 offset:1024
	ds_read_b128 v[168:171], v172 offset:2048
	ds_read_b128 v[172:175], v172 offset:3072
	v_lshl_add_u64 v[188:189], s[44:45], 0, v[140:141]
	s_add_i32 m0, s47, 0xc000
	ds_read_b128 v[176:179], v212
	ds_read_b128 v[180:183], v212 offset:1024
	ds_read_b128 v[184:187], v212 offset:2048
	ds_read_b128 v[214:217], v212 offset:3072
	ds_read_b128 v[218:221], v212 offset:4096
	ds_read_b128 v[222:225], v212 offset:5120
	ds_read_b128 v[226:229], v212 offset:6144
	ds_read_b128 v[230:233], v212 offset:7168
	global_load_lds_dwordx4 v[188:189], off
	v_lshl_add_u64 v[188:189], s[44:45], 0, v[142:143]
	s_add_i32 m0, s47, 0xe000
	s_nop 0
	global_load_lds_dwordx4 v[188:189], off
	s_waitcnt vmcnt(8)
	s_waitcnt lgkmcnt(0)
	s_barrier
	s_waitcnt lgkmcnt(0)
	v_mfma_f32_16x16x32_bf16 v[128:131], v[144:147], v[176:179], v[128:131]
	v_mfma_f32_16x16x32_bf16 v[124:127], v[152:155], v[176:179], v[124:127]
	v_mfma_f32_16x16x32_bf16 v[112:115], v[144:147], v[184:187], v[112:115]
	v_mfma_f32_16x16x32_bf16 v[108:111], v[152:155], v[184:187], v[108:111]
	v_mfma_f32_16x16x32_bf16 v[96:99], v[144:147], v[218:221], v[96:99]
	v_mfma_f32_16x16x32_bf16 v[92:95], v[152:155], v[218:221], v[92:95]
	v_mfma_f32_16x16x32_bf16 v[80:83], v[144:147], v[226:229], v[80:83]
	v_mfma_f32_16x16x32_bf16 v[76:79], v[152:155], v[226:229], v[76:79]
	v_mfma_f32_16x16x32_bf16 v[128:131], v[148:151], v[180:183], v[128:131]
	v_mfma_f32_16x16x32_bf16 v[124:127], v[156:159], v[180:183], v[124:127]
	v_mfma_f32_16x16x32_bf16 v[112:115], v[148:151], v[214:217], v[112:115]
	v_mfma_f32_16x16x32_bf16 v[108:111], v[156:159], v[214:217], v[108:111]
	v_mfma_f32_16x16x32_bf16 v[96:99], v[148:151], v[222:225], v[96:99]
	v_mfma_f32_16x16x32_bf16 v[92:95], v[156:159], v[222:225], v[92:95]
	v_mfma_f32_16x16x32_bf16 v[80:83], v[148:151], v[230:233], v[80:83]
	v_mfma_f32_16x16x32_bf16 v[76:79], v[156:159], v[230:233], v[76:79]
	v_mfma_f32_16x16x32_bf16 v[120:123], v[160:163], v[176:179], v[120:123]
	v_mfma_f32_16x16x32_bf16 v[116:119], v[168:171], v[176:179], v[116:119]
	v_mfma_f32_16x16x32_bf16 v[104:107], v[160:163], v[184:187], v[104:107]
	v_mfma_f32_16x16x32_bf16 v[100:103], v[168:171], v[184:187], v[100:103]
	v_mfma_f32_16x16x32_bf16 v[88:91], v[160:163], v[218:221], v[88:91]
	v_mfma_f32_16x16x32_bf16 v[84:87], v[168:171], v[218:221], v[84:87]
	v_mfma_f32_16x16x32_bf16 v[72:75], v[160:163], v[226:229], v[72:75]
	v_mfma_f32_16x16x32_bf16 v[68:71], v[168:171], v[226:229], v[68:71]
	v_mfma_f32_16x16x32_bf16 v[120:123], v[164:167], v[180:183], v[120:123]
	v_mfma_f32_16x16x32_bf16 v[116:119], v[172:175], v[180:183], v[116:119]
	v_mfma_f32_16x16x32_bf16 v[104:107], v[164:167], v[214:217], v[104:107]
	v_mfma_f32_16x16x32_bf16 v[100:103], v[172:175], v[214:217], v[100:103]
	v_mfma_f32_16x16x32_bf16 v[88:91], v[164:167], v[222:225], v[88:91]
	v_mfma_f32_16x16x32_bf16 v[84:87], v[172:175], v[222:225], v[84:87]
	v_mfma_f32_16x16x32_bf16 v[72:75], v[164:167], v[230:233], v[72:75]
	v_mfma_f32_16x16x32_bf16 v[68:71], v[172:175], v[230:233], v[68:71]
	s_barrier
	s_add_i32 s18, s18, s46
	v_lshl_add_u64 v[188:189], s[22:23], 0, v[2:3]
	s_mov_b32 m0, s18
	ds_read_b128 v[176:179], v212 offset:16384
	ds_read_b128 v[180:183], v212 offset:17408
	ds_read_b128 v[184:187], v212 offset:18432
	ds_read_b128 v[214:217], v212 offset:19456
	ds_read_b128 v[218:221], v212 offset:20480
	ds_read_b128 v[222:225], v212 offset:21504
	ds_read_b128 v[226:229], v212 offset:22528
	ds_read_b128 v[230:233], v212 offset:23552
	global_load_lds_dwordx4 v[188:189], off
	s_add_i32 m0, s18, 0x2000
	s_add_u32 s18, s22, 0xb0000
	v_lshl_add_u64 v[196:197], s[22:23], 0, v[0:1]
	s_addc_u32 s19, s23, 0
	s_add_i32 s44, s62, s46
	global_load_lds_dwordx4 v[196:197], off
	v_lshl_add_u64 v[198:199], s[18:19], 0, v[2:3]
	s_mov_b32 m0, s44
	v_lshl_add_u64 v[200:201], s[24:25], 0, v[0:1]
	global_load_lds_dwordx4 v[198:199], off
	v_lshl_add_u64 v[198:199], s[18:19], 0, v[0:1]
	s_add_i32 m0, s44, 0x2000
	s_nop 0
	global_load_lds_dwordx4 v[198:199], off
	v_lshl_add_u64 v[198:199], s[24:25], 0, v[2:3]
	s_mov_b32 m0, s47
	s_nop 0
	global_load_lds_dwordx4 v[198:199], off
	s_mov_b32 m0, s48
	s_nop 0
	global_load_lds_dwordx4 v[200:201], off
	s_waitcnt vmcnt(8)
	s_waitcnt lgkmcnt(0)
	s_barrier
	s_waitcnt lgkmcnt(0)
	v_mfma_f32_16x16x32_bf16 v[64:67], v[144:147], v[176:179], v[64:67]
	v_mfma_f32_16x16x32_bf16 v[60:63], v[152:155], v[176:179], v[60:63]
	v_mfma_f32_16x16x32_bf16 v[48:51], v[144:147], v[184:187], v[48:51]
	v_mfma_f32_16x16x32_bf16 v[44:47], v[152:155], v[184:187], v[44:47]
	v_mfma_f32_16x16x32_bf16 v[32:35], v[144:147], v[218:221], v[32:35]
	v_mfma_f32_16x16x32_bf16 v[28:31], v[152:155], v[218:221], v[28:31]
	v_mfma_f32_16x16x32_bf16 v[16:19], v[144:147], v[226:229], v[16:19]
	v_mfma_f32_16x16x32_bf16 v[12:15], v[152:155], v[226:229], v[12:15]
	v_mfma_f32_16x16x32_bf16 v[64:67], v[148:151], v[180:183], v[64:67]
	v_mfma_f32_16x16x32_bf16 v[60:63], v[156:159], v[180:183], v[60:63]
	v_mfma_f32_16x16x32_bf16 v[48:51], v[148:151], v[214:217], v[48:51]
	v_mfma_f32_16x16x32_bf16 v[44:47], v[156:159], v[214:217], v[44:47]
	v_mfma_f32_16x16x32_bf16 v[32:35], v[148:151], v[222:225], v[32:35]
	v_mfma_f32_16x16x32_bf16 v[28:31], v[156:159], v[222:225], v[28:31]
	v_mfma_f32_16x16x32_bf16 v[16:19], v[148:151], v[230:233], v[16:19]
	v_mfma_f32_16x16x32_bf16 v[12:15], v[156:159], v[230:233], v[12:15]
	v_mfma_f32_16x16x32_bf16 v[56:59], v[160:163], v[176:179], v[56:59]
	v_mfma_f32_16x16x32_bf16 v[52:55], v[168:171], v[176:179], v[52:55]
	v_mfma_f32_16x16x32_bf16 v[40:43], v[160:163], v[184:187], v[40:43]
	v_mfma_f32_16x16x32_bf16 v[36:39], v[168:171], v[184:187], v[36:39]
	v_mfma_f32_16x16x32_bf16 v[24:27], v[160:163], v[218:221], v[24:27]
	v_mfma_f32_16x16x32_bf16 v[20:23], v[168:171], v[218:221], v[20:23]
	v_mfma_f32_16x16x32_bf16 v[8:11], v[160:163], v[226:229], v[8:11]
	v_mfma_f32_16x16x32_bf16 v[4:7], v[168:171], v[226:229], v[4:7]
	v_mfma_f32_16x16x32_bf16 v[56:59], v[164:167], v[180:183], v[56:59]
	v_mfma_f32_16x16x32_bf16 v[52:55], v[172:175], v[180:183], v[52:55]
	v_mfma_f32_16x16x32_bf16 v[40:43], v[164:167], v[214:217], v[40:43]
	v_mfma_f32_16x16x32_bf16 v[36:39], v[172:175], v[214:217], v[36:39]
	v_mfma_f32_16x16x32_bf16 v[24:27], v[164:167], v[222:225], v[24:27]
	v_mfma_f32_16x16x32_bf16 v[20:23], v[172:175], v[222:225], v[20:23]
	v_mfma_f32_16x16x32_bf16 v[8:11], v[164:167], v[230:233], v[8:11]
	v_mfma_f32_16x16x32_bf16 v[4:7], v[172:175], v[230:233], v[4:7]
	s_barrier
	s_add_i32 s44, 0, 0x18000
	s_add_i32 s45, 0, 0x1c000
	v_add_u32_e32 v156, s44, v210
	v_add_u32_e32 v172, s45, v210
	ds_read_b128 v[144:147], v156
	ds_read_b128 v[148:151], v156 offset:1024
	ds_read_b128 v[152:155], v156 offset:2048
	ds_read_b128 v[156:159], v156 offset:3072
	ds_read_b128 v[160:163], v172
	ds_read_b128 v[164:167], v172 offset:1024
	ds_read_b128 v[168:171], v172 offset:2048
	ds_read_b128 v[172:175], v172 offset:3072
	s_add_u32 s18, s24, 0xb0000
	s_addc_u32 s19, s25, 0
	s_mov_b32 m0, s49
	v_lshl_add_u64 v[234:235], s[18:19], 0, v[2:3]
	ds_read_b128 v[176:179], v212 offset:32768
	ds_read_b128 v[180:183], v212 offset:33792
	ds_read_b128 v[184:187], v212 offset:34816
	ds_read_b128 v[214:217], v212 offset:35840
	ds_read_b128 v[218:221], v212 offset:36864
	ds_read_b128 v[222:225], v212 offset:37888
	ds_read_b128 v[226:229], v212 offset:38912
	ds_read_b128 v[230:233], v212 offset:39936
	global_load_lds_dwordx4 v[234:235], off
	v_lshl_add_u64 v[234:235], s[18:19], 0, v[0:1]
	s_mov_b32 m0, s50
	s_nop 0
	global_load_lds_dwordx4 v[234:235], off
	s_waitcnt vmcnt(8)
	s_waitcnt lgkmcnt(0)
	s_barrier
	s_waitcnt lgkmcnt(0)
	v_mfma_f32_16x16x32_bf16 v[128:131], v[144:147], v[176:179], v[128:131]
	v_mfma_f32_16x16x32_bf16 v[124:127], v[152:155], v[176:179], v[124:127]
	v_mfma_f32_16x16x32_bf16 v[112:115], v[144:147], v[184:187], v[112:115]
	v_mfma_f32_16x16x32_bf16 v[108:111], v[152:155], v[184:187], v[108:111]
	v_mfma_f32_16x16x32_bf16 v[96:99], v[144:147], v[218:221], v[96:99]
	v_mfma_f32_16x16x32_bf16 v[92:95], v[152:155], v[218:221], v[92:95]
	v_mfma_f32_16x16x32_bf16 v[80:83], v[144:147], v[226:229], v[80:83]
	v_mfma_f32_16x16x32_bf16 v[76:79], v[152:155], v[226:229], v[76:79]
	v_mfma_f32_16x16x32_bf16 v[128:131], v[148:151], v[180:183], v[128:131]
	v_mfma_f32_16x16x32_bf16 v[124:127], v[156:159], v[180:183], v[124:127]
	v_mfma_f32_16x16x32_bf16 v[112:115], v[148:151], v[214:217], v[112:115]
	v_mfma_f32_16x16x32_bf16 v[108:111], v[156:159], v[214:217], v[108:111]
	v_mfma_f32_16x16x32_bf16 v[96:99], v[148:151], v[222:225], v[96:99]
	v_mfma_f32_16x16x32_bf16 v[92:95], v[156:159], v[222:225], v[92:95]
	v_mfma_f32_16x16x32_bf16 v[80:83], v[148:151], v[230:233], v[80:83]
	v_mfma_f32_16x16x32_bf16 v[76:79], v[156:159], v[230:233], v[76:79]
	v_mfma_f32_16x16x32_bf16 v[120:123], v[160:163], v[176:179], v[120:123]
	v_mfma_f32_16x16x32_bf16 v[116:119], v[168:171], v[176:179], v[116:119]
	v_mfma_f32_16x16x32_bf16 v[104:107], v[160:163], v[184:187], v[104:107]
	v_mfma_f32_16x16x32_bf16 v[100:103], v[168:171], v[184:187], v[100:103]
	v_mfma_f32_16x16x32_bf16 v[88:91], v[160:163], v[218:221], v[88:91]
	v_mfma_f32_16x16x32_bf16 v[84:87], v[168:171], v[218:221], v[84:87]
	v_mfma_f32_16x16x32_bf16 v[72:75], v[160:163], v[226:229], v[72:75]
	v_mfma_f32_16x16x32_bf16 v[68:71], v[168:171], v[226:229], v[68:71]
	v_mfma_f32_16x16x32_bf16 v[120:123], v[164:167], v[180:183], v[120:123]
	v_mfma_f32_16x16x32_bf16 v[116:119], v[172:175], v[180:183], v[116:119]
	v_mfma_f32_16x16x32_bf16 v[104:107], v[164:167], v[214:217], v[104:107]
	v_mfma_f32_16x16x32_bf16 v[100:103], v[172:175], v[214:217], v[100:103]
	v_mfma_f32_16x16x32_bf16 v[88:91], v[164:167], v[222:225], v[88:91]
	v_mfma_f32_16x16x32_bf16 v[84:87], v[172:175], v[222:225], v[84:87]
	v_mfma_f32_16x16x32_bf16 v[72:75], v[164:167], v[230:233], v[72:75]
	v_mfma_f32_16x16x32_bf16 v[68:71], v[172:175], v[230:233], v[68:71]
	s_barrier
	s_add_i32 s18, s44, s46
	v_lshl_add_u64 v[188:189], v[188:189], 0, s[92:93]
	s_mov_b32 m0, s18
	ds_read_b128 v[176:179], v212 offset:49152
	ds_read_b128 v[180:183], v212 offset:50176
	ds_read_b128 v[184:187], v212 offset:51200
	ds_read_b128 v[214:217], v212 offset:52224
	ds_read_b128 v[218:221], v212 offset:53248
	ds_read_b128 v[222:225], v212 offset:54272
	ds_read_b128 v[226:229], v212 offset:55296
	ds_read_b128 v[230:233], v212 offset:56320
	global_load_lds_dwordx4 v[188:189], off
	s_add_i32 m0, s18, 0x2000
	s_add_u32 s18, s22, 0xb0080
	v_lshl_add_u64 v[188:189], v[196:197], 0, s[92:93]
	s_addc_u32 s19, s23, 0
	s_add_i32 s22, s45, s46
	global_load_lds_dwordx4 v[188:189], off
	v_lshl_add_u64 v[188:189], s[18:19], 0, v[2:3]
	s_mov_b32 m0, s22
	s_nop 0
	global_load_lds_dwordx4 v[188:189], off
	v_lshl_add_u64 v[188:189], s[18:19], 0, v[0:1]
	s_add_i32 m0, s22, 0x2000
	s_nop 0
	global_load_lds_dwordx4 v[188:189], off
	v_lshl_add_u64 v[188:189], v[198:199], 0, s[92:93]
	s_mov_b32 m0, s52
	s_nop 0
	global_load_lds_dwordx4 v[188:189], off
	v_lshl_add_u64 v[188:189], v[200:201], 0, s[92:93]
	s_mov_b32 m0, s53
	s_nop 0
	global_load_lds_dwordx4 v[188:189], off
	s_waitcnt vmcnt(8)
	s_waitcnt lgkmcnt(0)
	s_barrier
	s_waitcnt lgkmcnt(0)
	v_mfma_f32_16x16x32_bf16 v[64:67], v[144:147], v[176:179], v[64:67]
	v_mfma_f32_16x16x32_bf16 v[60:63], v[152:155], v[176:179], v[60:63]
	v_mfma_f32_16x16x32_bf16 v[48:51], v[144:147], v[184:187], v[48:51]
	v_mfma_f32_16x16x32_bf16 v[44:47], v[152:155], v[184:187], v[44:47]
	v_mfma_f32_16x16x32_bf16 v[32:35], v[144:147], v[218:221], v[32:35]
	v_mfma_f32_16x16x32_bf16 v[28:31], v[152:155], v[218:221], v[28:31]
	v_mfma_f32_16x16x32_bf16 v[16:19], v[144:147], v[226:229], v[16:19]
	v_mfma_f32_16x16x32_bf16 v[12:15], v[152:155], v[226:229], v[12:15]
	v_mfma_f32_16x16x32_bf16 v[64:67], v[148:151], v[180:183], v[64:67]
	v_mfma_f32_16x16x32_bf16 v[60:63], v[156:159], v[180:183], v[60:63]
	v_mfma_f32_16x16x32_bf16 v[48:51], v[148:151], v[214:217], v[48:51]
	v_mfma_f32_16x16x32_bf16 v[44:47], v[156:159], v[214:217], v[44:47]
	v_mfma_f32_16x16x32_bf16 v[32:35], v[148:151], v[222:225], v[32:35]
	v_mfma_f32_16x16x32_bf16 v[28:31], v[156:159], v[222:225], v[28:31]
	v_mfma_f32_16x16x32_bf16 v[16:19], v[148:151], v[230:233], v[16:19]
	v_mfma_f32_16x16x32_bf16 v[12:15], v[156:159], v[230:233], v[12:15]
	v_mfma_f32_16x16x32_bf16 v[56:59], v[160:163], v[176:179], v[56:59]
	v_mfma_f32_16x16x32_bf16 v[52:55], v[168:171], v[176:179], v[52:55]
	v_mfma_f32_16x16x32_bf16 v[40:43], v[160:163], v[184:187], v[40:43]
	v_mfma_f32_16x16x32_bf16 v[36:39], v[168:171], v[184:187], v[36:39]
	v_mfma_f32_16x16x32_bf16 v[24:27], v[160:163], v[218:221], v[24:27]
	v_mfma_f32_16x16x32_bf16 v[20:23], v[168:171], v[218:221], v[20:23]
	v_mfma_f32_16x16x32_bf16 v[8:11], v[160:163], v[226:229], v[8:11]
	v_mfma_f32_16x16x32_bf16 v[4:7], v[168:171], v[226:229], v[4:7]
	v_mfma_f32_16x16x32_bf16 v[56:59], v[164:167], v[180:183], v[56:59]
	v_mfma_f32_16x16x32_bf16 v[52:55], v[172:175], v[180:183], v[52:55]
	v_mfma_f32_16x16x32_bf16 v[40:43], v[164:167], v[214:217], v[40:43]
	v_mfma_f32_16x16x32_bf16 v[36:39], v[172:175], v[214:217], v[36:39]
	v_mfma_f32_16x16x32_bf16 v[24:27], v[164:167], v[222:225], v[24:27]
	v_mfma_f32_16x16x32_bf16 v[20:23], v[172:175], v[222:225], v[20:23]
	v_mfma_f32_16x16x32_bf16 v[8:11], v[164:167], v[230:233], v[8:11]
	v_mfma_f32_16x16x32_bf16 v[4:7], v[172:175], v[230:233], v[4:7]
	s_barrier
	s_add_i32 s15, s15, 2
	s_add_u32 s13, s13, 0x100
	s_addc_u32 s14, s14, 0
	s_cmp_gt_u32 s15, 41
	s_mov_b64 s[44:45], s[42:43]
	s_cbranch_scc0 .LBB0_811
	s_and_b64 vcc, exec, s[4:5]
	s_cbranch_vccz .LBB0_814
	s_barrier

.LBB0_928:
	s_add_u32 s18, s40, 0xfffc0080
	s_addc_u32 s19, s41, -1
	s_add_i32 s52, 0, 0x10000
	s_cmp_eq_u32 s51, 12
	s_cselect_b32 s25, s7, s19
	s_cselect_b32 s24, s13, s18
	s_cselect_b32 s23, s5, s43
	s_cselect_b32 s22, s17, s42
	s_add_i32 s53, 0, 0x14000
	v_add_u32_e32 v166, s52, v152
	v_add_u32_e32 v182, s53, v152
	ds_read_b128 v[148:151], v166
	ds_read_b128 v[158:161], v166 offset:1024
	ds_read_b128 v[162:165], v166 offset:2048
	ds_read_b128 v[166:169], v166 offset:3072
	ds_read_b128 v[170:173], v182
	ds_read_b128 v[174:177], v182 offset:1024
	ds_read_b128 v[178:181], v182 offset:2048
	ds_read_b128 v[182:185], v182 offset:3072
	v_lshl_add_u64 v[236:237], s[40:41], 0, v[144:145]
	s_add_i32 m0, s29, 0xc000
	ds_read_b128 v[186:189], v157
	ds_read_b128 v[208:211], v157 offset:1024
	ds_read_b128 v[212:215], v157 offset:2048
	ds_read_b128 v[216:219], v157 offset:3072
	ds_read_b128 v[220:223], v157 offset:4096
	ds_read_b128 v[224:227], v157 offset:5120
	ds_read_b128 v[228:231], v157 offset:6144
	ds_read_b128 v[232:235], v157 offset:7168
	global_load_lds_dwordx4 v[236:237], off
	v_lshl_add_u64 v[236:237], s[40:41], 0, v[146:147]
	s_add_i32 m0, s29, 0xe000
	s_nop 0
	global_load_lds_dwordx4 v[236:237], off
	s_waitcnt vmcnt(8)
	s_waitcnt lgkmcnt(0)
	s_barrier
	s_waitcnt lgkmcnt(0)
	v_mfma_f32_16x16x32_bf16 v[128:131], v[148:151], v[186:189], v[128:131]
	v_mfma_f32_16x16x32_bf16 v[124:127], v[162:165], v[186:189], v[124:127]
	v_mfma_f32_16x16x32_bf16 v[116:119], v[148:151], v[212:215], v[116:119]
	v_mfma_f32_16x16x32_bf16 v[108:111], v[162:165], v[212:215], v[108:111]
	v_mfma_f32_16x16x32_bf16 v[100:103], v[148:151], v[220:223], v[100:103]
	v_mfma_f32_16x16x32_bf16 v[92:95], v[162:165], v[220:223], v[92:95]
	v_mfma_f32_16x16x32_bf16 v[84:87], v[148:151], v[228:231], v[84:87]
	v_mfma_f32_16x16x32_bf16 v[76:79], v[162:165], v[228:231], v[76:79]
	v_mfma_f32_16x16x32_bf16 v[128:131], v[158:161], v[208:211], v[128:131]
	v_mfma_f32_16x16x32_bf16 v[124:127], v[166:169], v[208:211], v[124:127]
	v_mfma_f32_16x16x32_bf16 v[116:119], v[158:161], v[216:219], v[116:119]
	v_mfma_f32_16x16x32_bf16 v[108:111], v[166:169], v[216:219], v[108:111]
	v_mfma_f32_16x16x32_bf16 v[100:103], v[158:161], v[224:227], v[100:103]
	v_mfma_f32_16x16x32_bf16 v[92:95], v[166:169], v[224:227], v[92:95]
	v_mfma_f32_16x16x32_bf16 v[84:87], v[158:161], v[232:235], v[84:87]
	v_mfma_f32_16x16x32_bf16 v[76:79], v[166:169], v[232:235], v[76:79]
	v_mfma_f32_16x16x32_bf16 v[120:123], v[170:173], v[186:189], v[120:123]
	v_mfma_f32_16x16x32_bf16 v[112:115], v[178:181], v[186:189], v[112:115]
	v_mfma_f32_16x16x32_bf16 v[104:107], v[170:173], v[212:215], v[104:107]
	v_mfma_f32_16x16x32_bf16 v[96:99], v[178:181], v[212:215], v[96:99]
	v_mfma_f32_16x16x32_bf16 v[88:91], v[170:173], v[220:223], v[88:91]
	v_mfma_f32_16x16x32_bf16 v[80:83], v[178:181], v[220:223], v[80:83]
	v_mfma_f32_16x16x32_bf16 v[72:75], v[170:173], v[228:231], v[72:75]
	v_mfma_f32_16x16x32_bf16 v[68:71], v[178:181], v[228:231], v[68:71]
	v_mfma_f32_16x16x32_bf16 v[120:123], v[174:177], v[208:211], v[120:123]
	v_mfma_f32_16x16x32_bf16 v[112:115], v[182:185], v[208:211], v[112:115]
	v_mfma_f32_16x16x32_bf16 v[104:107], v[174:177], v[216:219], v[104:107]
	v_mfma_f32_16x16x32_bf16 v[96:99], v[182:185], v[216:219], v[96:99]
	v_mfma_f32_16x16x32_bf16 v[88:91], v[174:177], v[224:227], v[88:91]
	v_mfma_f32_16x16x32_bf16 v[80:83], v[182:185], v[224:227], v[80:83]
	v_mfma_f32_16x16x32_bf16 v[72:75], v[174:177], v[232:235], v[72:75]
	v_mfma_f32_16x16x32_bf16 v[68:71], v[182:185], v[232:235], v[68:71]
	s_barrier
	s_add_i32 s18, s52, s28
	v_lshl_add_u64 v[236:237], s[22:23], 0, v[2:3]
	s_mov_b32 m0, s18
	ds_read_b128 v[186:189], v157 offset:16384
	ds_read_b128 v[208:211], v157 offset:17408
	ds_read_b128 v[212:215], v157 offset:18432
	ds_read_b128 v[216:219], v157 offset:19456
	ds_read_b128 v[220:223], v157 offset:20480
	ds_read_b128 v[224:227], v157 offset:21504
	ds_read_b128 v[228:231], v157 offset:22528
	ds_read_b128 v[232:235], v157 offset:23552
	global_load_lds_dwordx4 v[236:237], off
	s_add_i32 m0, s18, 0x2000
	s_add_u32 s18, s22, 0x10000
	v_lshl_add_u64 v[238:239], s[22:23], 0, v[142:143]
	s_addc_u32 s19, s23, 0
	s_add_i32 s52, s53, s28
	global_load_lds_dwordx4 v[238:239], off
	v_lshl_add_u64 v[240:241], s[18:19], 0, v[2:3]
	s_mov_b32 m0, s52
	v_lshl_add_u64 v[242:243], s[24:25], 0, v[140:141]
	global_load_lds_dwordx4 v[240:241], off
	v_lshl_add_u64 v[240:241], s[18:19], 0, v[142:143]
	s_add_i32 m0, s52, 0x2000
	s_nop 0
	global_load_lds_dwordx4 v[240:241], off
	v_lshl_add_u64 v[240:241], s[24:25], 0, v[0:1]
	s_mov_b32 m0, s29
	s_nop 0
	global_load_lds_dwordx4 v[240:241], off
	s_mov_b32 m0, s44
	s_nop 0
	global_load_lds_dwordx4 v[242:243], off
	s_waitcnt vmcnt(8)
	s_waitcnt lgkmcnt(0)
	s_barrier
	s_waitcnt lgkmcnt(0)
	v_mfma_f32_16x16x32_bf16 v[64:67], v[148:151], v[186:189], v[64:67]
	v_mfma_f32_16x16x32_bf16 v[60:63], v[162:165], v[186:189], v[60:63]
	v_mfma_f32_16x16x32_bf16 v[52:55], v[148:151], v[212:215], v[52:55]
	v_mfma_f32_16x16x32_bf16 v[44:47], v[162:165], v[212:215], v[44:47]
	v_mfma_f32_16x16x32_bf16 v[36:39], v[148:151], v[220:223], v[36:39]
	v_mfma_f32_16x16x32_bf16 v[28:31], v[162:165], v[220:223], v[28:31]
	v_mfma_f32_16x16x32_bf16 v[20:23], v[148:151], v[228:231], v[20:23]
	v_mfma_f32_16x16x32_bf16 v[12:15], v[162:165], v[228:231], v[12:15]
	v_mfma_f32_16x16x32_bf16 v[64:67], v[158:161], v[208:211], v[64:67]
	v_mfma_f32_16x16x32_bf16 v[60:63], v[166:169], v[208:211], v[60:63]
	v_mfma_f32_16x16x32_bf16 v[52:55], v[158:161], v[216:219], v[52:55]
	v_mfma_f32_16x16x32_bf16 v[44:47], v[166:169], v[216:219], v[44:47]
	v_mfma_f32_16x16x32_bf16 v[36:39], v[158:161], v[224:227], v[36:39]
	v_mfma_f32_16x16x32_bf16 v[28:31], v[166:169], v[224:227], v[28:31]
	v_mfma_f32_16x16x32_bf16 v[20:23], v[158:161], v[232:235], v[20:23]
	v_mfma_f32_16x16x32_bf16 v[12:15], v[166:169], v[232:235], v[12:15]
	v_mfma_f32_16x16x32_bf16 v[56:59], v[170:173], v[186:189], v[56:59]
	v_mfma_f32_16x16x32_bf16 v[48:51], v[178:181], v[186:189], v[48:51]
	v_mfma_f32_16x16x32_bf16 v[40:43], v[170:173], v[212:215], v[40:43]
	v_mfma_f32_16x16x32_bf16 v[32:35], v[178:181], v[212:215], v[32:35]
	v_mfma_f32_16x16x32_bf16 v[24:27], v[170:173], v[220:223], v[24:27]
	v_mfma_f32_16x16x32_bf16 v[16:19], v[178:181], v[220:223], v[16:19]
	v_mfma_f32_16x16x32_bf16 v[8:11], v[170:173], v[228:231], v[8:11]
	v_mfma_f32_16x16x32_bf16 v[4:7], v[178:181], v[228:231], v[4:7]
	v_mfma_f32_16x16x32_bf16 v[56:59], v[174:177], v[208:211], v[56:59]
	v_mfma_f32_16x16x32_bf16 v[48:51], v[182:185], v[208:211], v[48:51]
	v_mfma_f32_16x16x32_bf16 v[40:43], v[174:177], v[216:219], v[40:43]
	v_mfma_f32_16x16x32_bf16 v[32:35], v[182:185], v[216:219], v[32:35]
	v_mfma_f32_16x16x32_bf16 v[24:27], v[174:177], v[224:227], v[24:27]
	v_mfma_f32_16x16x32_bf16 v[16:19], v[182:185], v[224:227], v[16:19]
	v_mfma_f32_16x16x32_bf16 v[8:11], v[174:177], v[232:235], v[8:11]
	v_mfma_f32_16x16x32_bf16 v[4:7], v[182:185], v[232:235], v[4:7]
	s_barrier
	s_add_i32 s52, 0, 0x18000
	s_add_i32 s53, 0, 0x1c000
	v_add_u32_e32 v166, s52, v152
	v_add_u32_e32 v182, s53, v152
	ds_read_b128 v[148:151], v166
	ds_read_b128 v[158:161], v166 offset:1024
	ds_read_b128 v[162:165], v166 offset:2048
	ds_read_b128 v[166:169], v166 offset:3072
	ds_read_b128 v[170:173], v182
	ds_read_b128 v[174:177], v182 offset:1024
	ds_read_b128 v[178:181], v182 offset:2048
	ds_read_b128 v[182:185], v182 offset:3072
	s_add_u32 s18, s24, 0x40000
	s_addc_u32 s19, s25, 0
	s_mov_b32 m0, s45
	v_lshl_add_u64 v[244:245], s[18:19], 0, v[0:1]
	ds_read_b128 v[186:189], v157 offset:32768
	ds_read_b128 v[208:211], v157 offset:33792
	ds_read_b128 v[212:215], v157 offset:34816
	ds_read_b128 v[216:219], v157 offset:35840
	ds_read_b128 v[220:223], v157 offset:36864
	ds_read_b128 v[224:227], v157 offset:37888
	ds_read_b128 v[228:231], v157 offset:38912
	ds_read_b128 v[232:235], v157 offset:39936
	global_load_lds_dwordx4 v[244:245], off
	v_lshl_add_u64 v[244:245], s[18:19], 0, v[140:141]
	s_mov_b32 m0, s46
	s_nop 0
	global_load_lds_dwordx4 v[244:245], off
	s_waitcnt vmcnt(8)
	s_waitcnt lgkmcnt(0)
	s_barrier
	s_waitcnt lgkmcnt(0)
	v_mfma_f32_16x16x32_bf16 v[128:131], v[148:151], v[186:189], v[128:131]
	v_mfma_f32_16x16x32_bf16 v[124:127], v[162:165], v[186:189], v[124:127]
	v_mfma_f32_16x16x32_bf16 v[116:119], v[148:151], v[212:215], v[116:119]
	v_mfma_f32_16x16x32_bf16 v[108:111], v[162:165], v[212:215], v[108:111]
	v_mfma_f32_16x16x32_bf16 v[100:103], v[148:151], v[220:223], v[100:103]
	v_mfma_f32_16x16x32_bf16 v[92:95], v[162:165], v[220:223], v[92:95]
	v_mfma_f32_16x16x32_bf16 v[84:87], v[148:151], v[228:231], v[84:87]
	v_mfma_f32_16x16x32_bf16 v[76:79], v[162:165], v[228:231], v[76:79]
	v_mfma_f32_16x16x32_bf16 v[128:131], v[158:161], v[208:211], v[128:131]
	v_mfma_f32_16x16x32_bf16 v[124:127], v[166:169], v[208:211], v[124:127]
	v_mfma_f32_16x16x32_bf16 v[116:119], v[158:161], v[216:219], v[116:119]
	v_mfma_f32_16x16x32_bf16 v[108:111], v[166:169], v[216:219], v[108:111]
	v_mfma_f32_16x16x32_bf16 v[100:103], v[158:161], v[224:227], v[100:103]
	v_mfma_f32_16x16x32_bf16 v[92:95], v[166:169], v[224:227], v[92:95]
	v_mfma_f32_16x16x32_bf16 v[84:87], v[158:161], v[232:235], v[84:87]
	v_mfma_f32_16x16x32_bf16 v[76:79], v[166:169], v[232:235], v[76:79]
	v_mfma_f32_16x16x32_bf16 v[120:123], v[170:173], v[186:189], v[120:123]
	v_mfma_f32_16x16x32_bf16 v[112:115], v[178:181], v[186:189], v[112:115]
	v_mfma_f32_16x16x32_bf16 v[104:107], v[170:173], v[212:215], v[104:107]
	v_mfma_f32_16x16x32_bf16 v[96:99], v[178:181], v[212:215], v[96:99]
	v_mfma_f32_16x16x32_bf16 v[88:91], v[170:173], v[220:223], v[88:91]
	v_mfma_f32_16x16x32_bf16 v[80:83], v[178:181], v[220:223], v[80:83]
	v_mfma_f32_16x16x32_bf16 v[72:75], v[170:173], v[228:231], v[72:75]
	v_mfma_f32_16x16x32_bf16 v[68:71], v[178:181], v[228:231], v[68:71]
	v_mfma_f32_16x16x32_bf16 v[120:123], v[174:177], v[208:211], v[120:123]
	v_mfma_f32_16x16x32_bf16 v[112:115], v[182:185], v[208:211], v[112:115]
	v_mfma_f32_16x16x32_bf16 v[104:107], v[174:177], v[216:219], v[104:107]
	v_mfma_f32_16x16x32_bf16 v[96:99], v[182:185], v[216:219], v[96:99]
	v_mfma_f32_16x16x32_bf16 v[88:91], v[174:177], v[224:227], v[88:91]
	v_mfma_f32_16x16x32_bf16 v[80:83], v[182:185], v[224:227], v[80:83]
	v_mfma_f32_16x16x32_bf16 v[72:75], v[174:177], v[232:235], v[72:75]
	v_mfma_f32_16x16x32_bf16 v[68:71], v[182:185], v[232:235], v[68:71]
	s_barrier
	s_add_i32 s18, s52, s28
	v_lshl_add_u64 v[236:237], v[236:237], 0, s[92:93]
	s_mov_b32 m0, s18
	ds_read_b128 v[186:189], v157 offset:49152
	ds_read_b128 v[208:211], v157 offset:50176
	ds_read_b128 v[212:215], v157 offset:51200
	ds_read_b128 v[216:219], v157 offset:52224
	ds_read_b128 v[220:223], v157 offset:53248
	ds_read_b128 v[224:227], v157 offset:54272
	ds_read_b128 v[228:231], v157 offset:55296
	ds_read_b128 v[232:235], v157 offset:56320
	global_load_lds_dwordx4 v[236:237], off
	s_add_i32 m0, s18, 0x2000
	s_add_u32 s18, s22, 0x10080
	v_lshl_add_u64 v[236:237], v[238:239], 0, s[92:93]
	s_addc_u32 s19, s23, 0
	s_add_i32 s22, s53, s28
	global_load_lds_dwordx4 v[236:237], off
	v_lshl_add_u64 v[236:237], s[18:19], 0, v[2:3]
	s_mov_b32 m0, s22
	s_nop 0
	global_load_lds_dwordx4 v[236:237], off
	v_lshl_add_u64 v[236:237], s[18:19], 0, v[142:143]
	s_add_i32 m0, s22, 0x2000
	s_nop 0
	global_load_lds_dwordx4 v[236:237], off
	v_lshl_add_u64 v[236:237], v[240:241], 0, s[92:93]
	s_mov_b32 m0, s47
	s_nop 0
	global_load_lds_dwordx4 v[236:237], off
	v_lshl_add_u64 v[236:237], v[242:243], 0, s[92:93]
	s_mov_b32 m0, s48
	s_nop 0
	global_load_lds_dwordx4 v[236:237], off
	s_waitcnt vmcnt(8)
	s_waitcnt lgkmcnt(0)
	s_barrier
	s_waitcnt lgkmcnt(0)
	v_mfma_f32_16x16x32_bf16 v[64:67], v[148:151], v[186:189], v[64:67]
	v_mfma_f32_16x16x32_bf16 v[60:63], v[162:165], v[186:189], v[60:63]
	v_mfma_f32_16x16x32_bf16 v[52:55], v[148:151], v[212:215], v[52:55]
	v_mfma_f32_16x16x32_bf16 v[44:47], v[162:165], v[212:215], v[44:47]
	v_mfma_f32_16x16x32_bf16 v[36:39], v[148:151], v[220:223], v[36:39]
	v_mfma_f32_16x16x32_bf16 v[28:31], v[162:165], v[220:223], v[28:31]
	v_mfma_f32_16x16x32_bf16 v[20:23], v[148:151], v[228:231], v[20:23]
	v_mfma_f32_16x16x32_bf16 v[12:15], v[162:165], v[228:231], v[12:15]
	v_mfma_f32_16x16x32_bf16 v[64:67], v[158:161], v[208:211], v[64:67]
	v_mfma_f32_16x16x32_bf16 v[60:63], v[166:169], v[208:211], v[60:63]
	v_mfma_f32_16x16x32_bf16 v[52:55], v[158:161], v[216:219], v[52:55]
	v_mfma_f32_16x16x32_bf16 v[44:47], v[166:169], v[216:219], v[44:47]
	v_mfma_f32_16x16x32_bf16 v[36:39], v[158:161], v[224:227], v[36:39]
	v_mfma_f32_16x16x32_bf16 v[28:31], v[166:169], v[224:227], v[28:31]
	v_mfma_f32_16x16x32_bf16 v[20:23], v[158:161], v[232:235], v[20:23]
	v_mfma_f32_16x16x32_bf16 v[12:15], v[166:169], v[232:235], v[12:15]
	v_mfma_f32_16x16x32_bf16 v[56:59], v[170:173], v[186:189], v[56:59]
	v_mfma_f32_16x16x32_bf16 v[48:51], v[178:181], v[186:189], v[48:51]
	v_mfma_f32_16x16x32_bf16 v[40:43], v[170:173], v[212:215], v[40:43]
	v_mfma_f32_16x16x32_bf16 v[32:35], v[178:181], v[212:215], v[32:35]
	v_mfma_f32_16x16x32_bf16 v[24:27], v[170:173], v[220:223], v[24:27]
	v_mfma_f32_16x16x32_bf16 v[16:19], v[178:181], v[220:223], v[16:19]
	v_mfma_f32_16x16x32_bf16 v[8:11], v[170:173], v[228:231], v[8:11]
	v_mfma_f32_16x16x32_bf16 v[4:7], v[178:181], v[228:231], v[4:7]
	v_mfma_f32_16x16x32_bf16 v[56:59], v[174:177], v[208:211], v[56:59]
	v_mfma_f32_16x16x32_bf16 v[48:51], v[182:185], v[208:211], v[48:51]
	v_mfma_f32_16x16x32_bf16 v[40:43], v[174:177], v[216:219], v[40:43]
	v_mfma_f32_16x16x32_bf16 v[32:35], v[182:185], v[216:219], v[32:35]
	v_mfma_f32_16x16x32_bf16 v[24:27], v[174:177], v[224:227], v[24:27]
	v_mfma_f32_16x16x32_bf16 v[16:19], v[182:185], v[224:227], v[16:19]
	v_mfma_f32_16x16x32_bf16 v[8:11], v[174:177], v[232:235], v[8:11]
	v_mfma_f32_16x16x32_bf16 v[4:7], v[182:185], v[232:235], v[4:7]
	s_barrier
	s_add_i32 s51, s51, 2
	s_add_u32 s40, s40, 0x100
	s_addc_u32 s41, s41, 0
	s_add_u32 s42, s42, 0x100
	s_addc_u32 s43, s43, 0
	s_cmp_gt_u32 s51, 13
	s_cbranch_scc0 .LBB0_928
	s_lshl_b32 s5, s16, 8
	s_and_b64 vcc, exec, s[2:3]
	s_cbranch_vccz .LBB0_931
	v_or_b32_e32 v148, s5, v154
	v_ashrrev_i32_e32 v149, 31, v148
	v_lshlrev_b64 v[148:149], 6, v[148:149]
	v_lshl_add_u64 v[166:167], s[74:75], 0, v[148:149]
	global_load_dwordx4 v[148:151], v[166:167], off
	global_load_dwordx4 v[158:161], v[166:167], off offset:32
	global_load_dwordx4 v[162:165], v[166:167], off offset:16
	s_nop 0
	global_load_dwordx4 v[166:169], v[166:167], off offset:48
	s_barrier
